# conv_stage1 branch-weight tiles and LRU gate-weight units: one pointer load and 16 (8) value loads in flight instead of a serialized pointer+value round trip per row
# baseline (speedup 1.0000x reference)
; DI int tidx() { int t = __builtin_amdgcn_workitem_id_x(); asm volatile("" : "+v"(t)); return t; }
; DI void conv_stage1(KP p, int l, int u, char* smem) {
;     ...
;   for (int e = 0; e < 8; ++e) {
;     int idx = (u * 8 + e) * 256 + tidx();
;     int g = idx >> 14, n = (idx >> 6) & 255, i = idx & 63;
;     int mat = n >> 6, j = n & 63, dir = mat >> 1;
;     const float* src = (mat & 1) ? p->lru_wx : p->lru_wa;
;     W[W_LRU + idx] = f2bf(src[((((size_t)l * 2 + dir) * 8 + g) * 64 + i) * 64 + j]);
.LBB0_131:
	s_and_b64 vcc, exec, s[8:9]
	s_cbranch_vccz .LBB0_248
	s_mov_b64 s[24:25], s[0:1]
	s_load_dwordx2 s[26:27], s[24:25], 0x130
	s_add_i32 s35, s34, 0xffffef00
	s_mov_b64 s[8:9], -1
	s_waitcnt lgkmcnt(0)
	s_add_u32 s18, s26, 0xd150000
	s_addc_u32 s19, s27, 0
	s_cmpk_gt_u32 s35, 0x33f
	s_cbranch_scc0 .LBB0_235
	s_cmpk_gt_u32 s35, 0x63f
	s_cbranch_scc0 .LBB0_232
	s_cmpk_gt_u32 s35, 0x687
	s_cbranch_scc0 .LBB0_229
	s_cmpk_gt_u32 s35, 0x6c7
	s_cbranch_scc0 .LBB0_226
	s_cmpk_gt_u32 s35, 0x847
	s_cbranch_scc0 .LBB0_142
	s_cmpk_lt_u32 s35, 0x948
	s_cbranch_scc1 .LBB0_139
	s_lshl_b32 s2, s35, 11
	v_mov_b32_e32 v8, 0x88
	v_mov_b32_e32 v9, 0x78
	s_mov_b32 s4, 0x1290000
	s_add_i32 s3, s2, 0xffb5c000
	v_add_u32_e32 v106, s3, v0
	v_and_b32_e32 v5, 0x1000, v106
	v_cmp_eq_u32_e32 vcc, 0, v5
	v_ashrrev_i32_e32 v156, 14, v106
	v_lshrrev_b32_e32 v5, 10, v106
	v_cndmask_b32_e32 v198, v8, v9, vcc
	v_lshl_add_u64 v[132:133], s[24:25], 0, v[198:199]
	global_load_dwordx2 v[132:133], v[132:133], off
	v_and_or_b32 v198, v5, 8, s21
	v_ashrrev_i32_e32 v157, 31, v156
	v_lshl_add_u64 v[156:157], v[198:199], 0, v[156:157]
	v_lshlrev_b64 v[156:157], 14, v[156:157]
	s_add_i32 s3, s2, 0xffb5c100
	v_add_u32_e32 v107, s3, v0
	v_and_b32_e32 v5, 0x1000, v107
	v_cmp_eq_u32_e32 vcc, 0, v5
	v_ashrrev_i32_e32 v158, 14, v107
	v_lshrrev_b32_e32 v5, 10, v107
	v_cndmask_b32_e32 v198, v8, v9, vcc
	v_lshl_add_u64 v[134:135], s[24:25], 0, v[198:199]
	global_load_dwordx2 v[134:135], v[134:135], off
	v_and_or_b32 v198, v5, 8, s21
	v_ashrrev_i32_e32 v159, 31, v158
	v_lshl_add_u64 v[158:159], v[198:199], 0, v[158:159]
	v_lshlrev_b64 v[158:159], 14, v[158:159]
	s_add_i32 s3, s2, 0xffb5c200
	v_add_u32_e32 v108, s3, v0
	v_and_b32_e32 v5, 0x1000, v108
	v_cmp_eq_u32_e32 vcc, 0, v5
	v_ashrrev_i32_e32 v160, 14, v108
	v_lshrrev_b32_e32 v5, 10, v108
	v_cndmask_b32_e32 v198, v8, v9, vcc
	v_lshl_add_u64 v[136:137], s[24:25], 0, v[198:199]
	global_load_dwordx2 v[136:137], v[136:137], off
	v_and_or_b32 v198, v5, 8, s21
	v_ashrrev_i32_e32 v161, 31, v160
	v_lshl_add_u64 v[160:161], v[198:199], 0, v[160:161]
	v_lshlrev_b64 v[160:161], 14, v[160:161]
	s_add_i32 s3, s2, 0xffb5c300
	v_add_u32_e32 v109, s3, v0
	v_and_b32_e32 v5, 0x1000, v109
	v_cmp_eq_u32_e32 vcc, 0, v5
	v_ashrrev_i32_e32 v162, 14, v109
	v_lshrrev_b32_e32 v5, 10, v109
	v_cndmask_b32_e32 v198, v8, v9, vcc
	v_lshl_add_u64 v[138:139], s[24:25], 0, v[198:199]
	global_load_dwordx2 v[138:139], v[138:139], off
	v_and_or_b32 v198, v5, 8, s21
	v_ashrrev_i32_e32 v163, 31, v162
	v_lshl_add_u64 v[162:163], v[198:199], 0, v[162:163]
	v_lshlrev_b64 v[162:163], 14, v[162:163]
	s_add_i32 s3, s2, 0xffb5c400
	v_add_u32_e32 v110, s3, v0
	v_and_b32_e32 v5, 0x1000, v110
	v_cmp_eq_u32_e32 vcc, 0, v5
	v_ashrrev_i32_e32 v164, 14, v110
	v_lshrrev_b32_e32 v5, 10, v110
	v_cndmask_b32_e32 v198, v8, v9, vcc
	v_lshl_add_u64 v[140:141], s[24:25], 0, v[198:199]
	global_load_dwordx2 v[140:141], v[140:141], off
	v_and_or_b32 v198, v5, 8, s21
	v_ashrrev_i32_e32 v165, 31, v164
	v_lshl_add_u64 v[164:165], v[198:199], 0, v[164:165]
	v_lshlrev_b64 v[164:165], 14, v[164:165]
	s_add_i32 s3, s2, 0xffb5c500
	v_add_u32_e32 v111, s3, v0
	v_and_b32_e32 v5, 0x1000, v111
	v_cmp_eq_u32_e32 vcc, 0, v5
	v_ashrrev_i32_e32 v166, 14, v111
	v_lshrrev_b32_e32 v5, 10, v111
	v_cndmask_b32_e32 v198, v8, v9, vcc
	v_lshl_add_u64 v[142:143], s[24:25], 0, v[198:199]
	global_load_dwordx2 v[142:143], v[142:143], off
	v_and_or_b32 v198, v5, 8, s21
	v_ashrrev_i32_e32 v167, 31, v166
	v_lshl_add_u64 v[166:167], v[198:199], 0, v[166:167]
	v_lshlrev_b64 v[166:167], 14, v[166:167]
	s_add_i32 s3, s2, 0xffb5c600
	v_add_u32_e32 v112, s3, v0
	v_and_b32_e32 v5, 0x1000, v112
	v_cmp_eq_u32_e32 vcc, 0, v5
	v_ashrrev_i32_e32 v168, 14, v112
	v_lshrrev_b32_e32 v5, 10, v112
	v_cndmask_b32_e32 v198, v8, v9, vcc
	v_lshl_add_u64 v[144:145], s[24:25], 0, v[198:199]
	global_load_dwordx2 v[144:145], v[144:145], off
	v_and_or_b32 v198, v5, 8, s21
	v_ashrrev_i32_e32 v169, 31, v168
	v_lshl_add_u64 v[168:169], v[198:199], 0, v[168:169]
	v_lshlrev_b64 v[168:169], 14, v[168:169]
	s_add_i32 s3, s2, 0xffb5c700
	v_add_u32_e32 v113, s3, v0
	v_and_b32_e32 v5, 0x1000, v113
	v_cmp_eq_u32_e32 vcc, 0, v5
	v_ashrrev_i32_e32 v170, 14, v113
	v_lshrrev_b32_e32 v5, 10, v113
	v_cndmask_b32_e32 v198, v8, v9, vcc
	v_lshl_add_u64 v[146:147], s[24:25], 0, v[198:199]
	global_load_dwordx2 v[146:147], v[146:147], off
	v_and_or_b32 v198, v5, 8, s21
	v_ashrrev_i32_e32 v171, 31, v170
	v_lshl_add_u64 v[170:171], v[198:199], 0, v[170:171]
	v_lshlrev_b64 v[170:171], 14, v[170:171]
	v_lshlrev_b32_e32 v3, 8, v0
	v_and_b32_e32 v6, 0x3f00, v3
	s_waitcnt vmcnt(7)
; DI int tidx() { int t = __builtin_amdgcn_workitem_id_x(); asm volatile("" : "+v"(t)); return t; }
; DI void conv_stage1(KP p, int l, int u, char* smem) {
;     ...
;   for (int e = 0; e < 8; ++e) {
;     int idx = (u * 8 + e) * 256 + tidx();
;     int g = idx >> 14, n = (idx >> 6) & 255, i = idx & 63;
;     int mat = n >> 6, j = n & 63, dir = mat >> 1;
;     const float* src = (mat & 1) ? p->lru_wx : p->lru_wa;
;     W[W_LRU + idx] = f2bf(src[((((size_t)l * 2 + dir) * 8 + g) * 64 + i) * 64 + j]);
;   }
	v_lshl_add_u64 v[156:157], v[132:133], 0, v[156:157]
	v_lshrrev_b32_e32 v3, 4, v106
	v_mov_b32_e32 v198, v6
	v_lshl_add_u64 v[156:157], v[156:157], 0, v[198:199]
	v_and_b32_e32 v198, 0xfc, v3
	v_lshl_add_u64 v[156:157], v[156:157], 0, v[198:199]
	global_load_dword v148, v[156:157], off
	s_waitcnt vmcnt(7)
	v_lshl_add_u64 v[158:159], v[134:135], 0, v[158:159]
	v_lshrrev_b32_e32 v3, 4, v107
	v_mov_b32_e32 v198, v6
	v_lshl_add_u64 v[158:159], v[158:159], 0, v[198:199]
	v_and_b32_e32 v198, 0xfc, v3
	v_lshl_add_u64 v[158:159], v[158:159], 0, v[198:199]
	global_load_dword v149, v[158:159], off
	s_waitcnt vmcnt(7)
	v_lshl_add_u64 v[160:161], v[136:137], 0, v[160:161]
	v_lshrrev_b32_e32 v3, 4, v108
	v_mov_b32_e32 v198, v6
	v_lshl_add_u64 v[160:161], v[160:161], 0, v[198:199]
	v_and_b32_e32 v198, 0xfc, v3
	v_lshl_add_u64 v[160:161], v[160:161], 0, v[198:199]
	global_load_dword v150, v[160:161], off
	s_waitcnt vmcnt(7)
	v_lshl_add_u64 v[162:163], v[138:139], 0, v[162:163]
	v_lshrrev_b32_e32 v3, 4, v109
	v_mov_b32_e32 v198, v6
	v_lshl_add_u64 v[162:163], v[162:163], 0, v[198:199]
	v_and_b32_e32 v198, 0xfc, v3
	v_lshl_add_u64 v[162:163], v[162:163], 0, v[198:199]
	global_load_dword v151, v[162:163], off
	s_waitcnt vmcnt(7)
	v_lshl_add_u64 v[164:165], v[140:141], 0, v[164:165]
	v_lshrrev_b32_e32 v3, 4, v110
	v_mov_b32_e32 v198, v6
	v_lshl_add_u64 v[164:165], v[164:165], 0, v[198:199]
	v_and_b32_e32 v198, 0xfc, v3
	v_lshl_add_u64 v[164:165], v[164:165], 0, v[198:199]
	global_load_dword v152, v[164:165], off
	s_waitcnt vmcnt(7)
	v_lshl_add_u64 v[166:167], v[142:143], 0, v[166:167]
	v_lshrrev_b32_e32 v3, 4, v111
	v_mov_b32_e32 v198, v6
	v_lshl_add_u64 v[166:167], v[166:167], 0, v[198:199]
	v_and_b32_e32 v198, 0xfc, v3
	v_lshl_add_u64 v[166:167], v[166:167], 0, v[198:199]
	global_load_dword v153, v[166:167], off
	s_waitcnt vmcnt(7)
	v_lshl_add_u64 v[168:169], v[144:145], 0, v[168:169]
	v_lshrrev_b32_e32 v3, 4, v112
	v_mov_b32_e32 v198, v6
	v_lshl_add_u64 v[168:169], v[168:169], 0, v[198:199]
	v_and_b32_e32 v198, 0xfc, v3
	v_lshl_add_u64 v[168:169], v[168:169], 0, v[198:199]
	global_load_dword v154, v[168:169], off
	s_waitcnt vmcnt(7)
	v_lshl_add_u64 v[170:171], v[146:147], 0, v[170:171]
	v_lshrrev_b32_e32 v3, 4, v113
	v_mov_b32_e32 v198, v6
	v_lshl_add_u64 v[170:171], v[170:171], 0, v[198:199]
	v_and_b32_e32 v198, 0xfc, v3
	v_lshl_add_u64 v[170:171], v[170:171], 0, v[198:199]
	global_load_dword v155, v[170:171], off
	v_ashrrev_i32_e32 v173, 31, v106
	v_mov_b32_e32 v172, v106
	v_lshl_add_u64 v[172:173], v[172:173], 1, s[18:19]
	v_add_co_u32_e32 v172, vcc, s4, v172
	s_nop 1
	v_addc_co_u32_e32 v173, vcc, 0, v173, vcc
	s_waitcnt vmcnt(7)
	v_cvt_pk_bf16_f32 v148, v148, v148
	global_store_short v[172:173], v148, off
	v_ashrrev_i32_e32 v175, 31, v107
	v_mov_b32_e32 v174, v107
	v_lshl_add_u64 v[174:175], v[174:175], 1, s[18:19]
	v_add_co_u32_e32 v174, vcc, s4, v174
	s_nop 1
	v_addc_co_u32_e32 v175, vcc, 0, v175, vcc
	s_waitcnt vmcnt(7)
	v_cvt_pk_bf16_f32 v149, v149, v149
	global_store_short v[174:175], v149, off
	v_ashrrev_i32_e32 v177, 31, v108
	v_mov_b32_e32 v176, v108
	v_lshl_add_u64 v[176:177], v[176:177], 1, s[18:19]
	v_add_co_u32_e32 v176, vcc, s4, v176
	s_nop 1
	v_addc_co_u32_e32 v177, vcc, 0, v177, vcc
	s_waitcnt vmcnt(7)
	v_cvt_pk_bf16_f32 v150, v150, v150
	global_store_short v[176:177], v150, off
	v_ashrrev_i32_e32 v179, 31, v109
	v_mov_b32_e32 v178, v109
	v_lshl_add_u64 v[178:179], v[178:179], 1, s[18:19]
	v_add_co_u32_e32 v178, vcc, s4, v178
	s_nop 1
	v_addc_co_u32_e32 v179, vcc, 0, v179, vcc
	s_waitcnt vmcnt(7)
	v_cvt_pk_bf16_f32 v151, v151, v151
	global_store_short v[178:179], v151, off
	v_ashrrev_i32_e32 v181, 31, v110
	v_mov_b32_e32 v180, v110
	v_lshl_add_u64 v[180:181], v[180:181], 1, s[18:19]
	v_add_co_u32_e32 v180, vcc, s4, v180
	s_nop 1
	v_addc_co_u32_e32 v181, vcc, 0, v181, vcc
	s_waitcnt vmcnt(7)
	v_cvt_pk_bf16_f32 v152, v152, v152
	global_store_short v[180:181], v152, off
	v_ashrrev_i32_e32 v183, 31, v111
	v_mov_b32_e32 v182, v111
	v_lshl_add_u64 v[182:183], v[182:183], 1, s[18:19]
	v_add_co_u32_e32 v182, vcc, s4, v182
	s_nop 1
	v_addc_co_u32_e32 v183, vcc, 0, v183, vcc
	s_waitcnt vmcnt(7)
	v_cvt_pk_bf16_f32 v153, v153, v153
	global_store_short v[182:183], v153, off
	v_ashrrev_i32_e32 v185, 31, v112
	v_mov_b32_e32 v184, v112
	v_lshl_add_u64 v[184:185], v[184:185], 1, s[18:19]
	v_add_co_u32_e32 v184, vcc, s4, v184
	s_nop 1
	v_addc_co_u32_e32 v185, vcc, 0, v185, vcc
	s_waitcnt vmcnt(7)
	v_cvt_pk_bf16_f32 v154, v154, v154
	global_store_short v[184:185], v154, off
	v_ashrrev_i32_e32 v187, 31, v113
	v_mov_b32_e32 v186, v113
	v_lshl_add_u64 v[186:187], v[186:187], 1, s[18:19]
	v_add_co_u32_e32 v186, vcc, s4, v186
	s_nop 1
	v_addc_co_u32_e32 v187, vcc, 0, v187, vcc
	s_waitcnt vmcnt(7)
	v_cvt_pk_bf16_f32 v155, v155, v155
	global_store_short v[186:187], v155, off
	s_mov_b64 s[8:9], 0

; DI int tidx() { int t = __builtin_amdgcn_workitem_id_x(); asm volatile("" : "+v"(t)); return t; }
; DI unsigned pack2(float lo, float hi) { f32x2 v; v.x = lo; v.y = hi; return __builtin_bit_cast(unsigned, __builtin_convertvector(v, hwbf2)); }
; DI float wsrc(KP p, int job, int l, int k, int n) {
;     ...
;     case J_WBRA: return p->w_br_a[((size_t)l * 512 + k) * 1024 + n];
;     case J_WBRB: return p->w_br_b[((size_t)l * 512 + k) * 1024 + n];
;     case J_WBRC: return p->w_br_c[((size_t)l * 512 + k) * 1024 + n];
; DI void conv_tile(KP p, u16* dst, int K, int job, int l, int nt, int kt, char* smem) {
;   float* tile = (float*)smem;
;   const int tid = tidx();
;   __syncthreads();
;   {
;     const int n = nt * 64 + (tid & 63), kb = kt * 64 + (tid >> 6) * 16;
; #pragma unroll
;     for (int i = 0; i < 16; ++i) tile[((tid >> 6) * 16 + i) * 65 + (tid & 63)] = wsrc(p, job, l, kb + i, n);
;   }
;   __syncthreads();
;   {
;     const int nl = tid >> 2, kq = (tid & 3) * 16;
;     unsigned v[8];
; #pragma unroll
;     for (int j = 0; j < 8; ++j) v[j] = pack2(tile[(kq + 2 * j) * 65 + nl], tile[(kq + 2 * j + 1) * 65 + nl]);
;     u16* d = dst + (size_t)(nt * 64 + nl) * K + kt * 64 + kq;
;     *(u32x4*)d = u32x4{v[0], v[1], v[2], v[3]};
;     *(u32x4*)(d + 8) = u32x4{v[4], v[5], v[6], v[7]};
;   }
.LBB0_148:
	s_lshl_b32 s2, s2, 3
	s_and_b32 s3, s2, 0x3c0
	s_lshl_b32 s2, s35, 6
	v_ashrrev_i32_e32 v7, 2, v3
	s_and_b32 s2, s2, 0x1c0
	v_and_b32_e32 v10, -16, v7
	s_load_dwordx2 s[4:5], s[22:23], 0x0
	v_add_u32_e32 v4, s2, v10
	v_ashrrev_i32_e32 v5, 31, v4
	v_and_b32_e32 v2, 63, v3
	v_lshl_add_u64 v[8:9], v[4:5], 0, s[80:81]
	v_or_b32_e32 v6, s3, v2
	v_lshlrev_b64 v[8:9], 12, v[8:9]
	s_waitcnt lgkmcnt(0)
	v_lshl_add_u64 v[8:9], s[4:5], 0, v[8:9]
	v_lshlrev_b32_e32 v198, 2, v6
	v_lshl_add_u64 v[8:9], v[8:9], 0, v[198:199]
	v_add_u32_e32 v148, s80, v4
	v_lshlrev_b32_e32 v2, 2, v2
	v_lshlrev_b32_e32 v148, 12, v148
	v_mul_lo_u32 v5, v10, s54
	v_add_u32_e32 v148, v148, v198
	v_add_u32_e32 v5, v2, v5
	global_load_dword v106, v148, s[4:5]
	v_add_u32_e32 v133, 0x1000, v148
	global_load_dword v107, v133, s[4:5]
	v_add_u32_e32 v134, 0x2000, v148
	global_load_dword v108, v134, s[4:5]
	v_add_u32_e32 v135, 0x3000, v148
	global_load_dword v109, v135, s[4:5]
	v_add_u32_e32 v136, 0x4000, v148
	global_load_dword v110, v136, s[4:5]
	v_add_u32_e32 v137, 0x5000, v148
	global_load_dword v111, v137, s[4:5]
	v_add_u32_e32 v138, 0x6000, v148
	global_load_dword v112, v138, s[4:5]
	v_add_u32_e32 v139, 0x7000, v148
	global_load_dword v113, v139, s[4:5]
	v_add_u32_e32 v140, 0x8000, v148
	global_load_dword v114, v140, s[4:5]
	v_add_u32_e32 v141, 0x9000, v148
	global_load_dword v115, v141, s[4:5]
	v_add_u32_e32 v142, 0xa000, v148
	global_load_dword v116, v142, s[4:5]
	v_add_u32_e32 v143, 0xb000, v148
	global_load_dword v117, v143, s[4:5]
	v_add_u32_e32 v144, 0xc000, v148
	global_load_dword v118, v144, s[4:5]
	v_add_u32_e32 v145, 0xd000, v148
	global_load_dword v119, v145, s[4:5]
	v_add_u32_e32 v146, 0xe000, v148
	global_load_dword v120, v146, s[4:5]
	v_add_u32_e32 v147, 0xf000, v148
	global_load_dword v121, v147, s[4:5]
	s_waitcnt vmcnt(15)
	ds_write_b32 v5, v106
	s_waitcnt vmcnt(14)
	ds_write_b32 v5, v107 offset:260
	s_waitcnt vmcnt(13)
	ds_write_b32 v5, v108 offset:520
	s_waitcnt vmcnt(12)
	ds_write_b32 v5, v109 offset:780
	s_waitcnt vmcnt(11)
	ds_write_b32 v5, v110 offset:1040
	s_waitcnt vmcnt(10)
	ds_write_b32 v5, v111 offset:1300
	s_waitcnt vmcnt(9)
	ds_write_b32 v5, v112 offset:1560
	s_waitcnt vmcnt(8)
	ds_write_b32 v5, v113 offset:1820
	s_waitcnt vmcnt(7)
	ds_write_b32 v5, v114 offset:2080
	s_waitcnt vmcnt(6)
	ds_write_b32 v5, v115 offset:2340
	s_waitcnt vmcnt(5)
	ds_write_b32 v5, v116 offset:2600
	s_waitcnt vmcnt(4)
	ds_write_b32 v5, v117 offset:2860
	s_waitcnt vmcnt(3)
	ds_write_b32 v5, v118 offset:3120
	s_waitcnt vmcnt(2)
	ds_write_b32 v5, v119 offset:3380
	s_waitcnt vmcnt(1)
	ds_write_b32 v5, v120 offset:3640
	s_waitcnt vmcnt(0)
	ds_write_b32 v5, v121 offset:3900
	s_lshl_b64 s[4:5], s[40:41], 20
	v_add_u32_e32 v4, s3, v7
	v_lshlrev_b32_e32 v8, 4, v3
	s_add_u32 s4, s26, s4
	v_ashrrev_i32_e32 v5, 31, v4
	v_and_b32_e32 v3, 48, v8
	s_addc_u32 s5, s27, s5
	v_lshlrev_b64 v[4:5], 10, v[4:5]
	v_mul_u32_u24_e32 v8, 0x41, v3
	s_lshl_b32 s40, s2, 1
	v_lshl_add_u64 v[4:5], s[4:5], 0, v[4:5]
	v_lshlrev_b32_e32 v8, 2, v8
	v_lshl_add_u64 v[4:5], v[4:5], 0, s[40:41]
	v_lshlrev_b32_e32 v198, 1, v3
	v_lshl_add_u32 v7, v7, 2, v8
	v_lshl_add_u64 v[4:5], v[4:5], 0, v[198:199]
	v_add_u32_e32 v8, 0x400, v7
	v_add_u32_e32 v16, 0x800, v7
	v_add_u32_e32 v20, 0xc00, v7
	s_mov_b64 s[2:3], 0xdee0000
	v_add_co_u32_e32 v12, vcc, 0xdee0000, v4
	v_lshl_add_u64 v[10:11], v[4:5], 0, s[2:3]
	s_nop 0
	v_addc_co_u32_e32 v13, vcc, 0, v5, vcc
	s_waitcnt lgkmcnt(0)
	s_barrier
	ds_read2_b32 v[2:3], v7 offset1:65
	ds_read2_b32 v[4:5], v7 offset0:130 offset1:195
	ds_read2_b32 v[6:7], v8 offset0:4 offset1:69
	ds_read2_b32 v[8:9], v8 offset0:134 offset1:199
	ds_read2_b32 v[14:15], v16 offset0:8 offset1:73
	ds_read2_b32 v[16:17], v16 offset0:138 offset1:203
	ds_read2_b32 v[18:19], v20 offset0:12 offset1:77
	ds_read2_b32 v[20:21], v20 offset0:142 offset1:207
	s_waitcnt lgkmcnt(7)
	v_cvt_pk_bf16_f32 v2, v2, v3
	s_waitcnt lgkmcnt(6)
	v_cvt_pk_bf16_f32 v3, v4, v5
	s_waitcnt lgkmcnt(5)
	v_cvt_pk_bf16_f32 v4, v6, v7
	s_waitcnt lgkmcnt(4)
	v_cvt_pk_bf16_f32 v5, v8, v9
	s_waitcnt lgkmcnt(3)
	v_cvt_pk_bf16_f32 v6, v14, v15
	s_waitcnt lgkmcnt(2)
	v_cvt_pk_bf16_f32 v7, v16, v17
	s_waitcnt lgkmcnt(1)
	v_cvt_pk_bf16_f32 v8, v18, v19
	s_waitcnt lgkmcnt(0)
	v_cvt_pk_bf16_f32 v9, v20, v21
	global_store_dwordx4 v[12:13], v[2:5], off
	global_store_dwordx4 v[10:11], v[6:9], off offset:16
